# SSD LDS XOR swizzle (conflict-free ds_read_b128 fragments) + attention hoist + norm + ssd S2 + xcd map
# speedup vs baseline: 1.0262x; 1.0028x over previous
; #define LAS __attribute__((address_space(3)))
; __device__ __forceinline__ float bflo(unsigned w) { return __uint_as_float(w << 16); }
; __device__ __forceinline__ void ssd_item(const Args& a, LAS unsigned char* lds, int layer, bool is_sample, int b, int h, int seq_row0, int nchunks,
;                                          bf16_t* proj, float* ssq, const int tid) {
;     ...
;             for (int k = 0; k < 4; ++k) { const u32x4 w = *(const LAS u32x4*)(lds + L_XRAW + (lane + k) * P64 + wave * 16);
;                 o[0] += cw[k][0] * bflo(w.x); o[1] += cw[k][1] * bfhi(w.x); o[2] += cw[k][2] * bflo(w.y); o[3] += cw[k][3] * bfhi(w.y);
;                 o[4] += cw[k][4] * bflo(w.z); o[5] += cw[k][5] * bfhi(w.z); o[6] += cw[k][6] * bflo(w.w); o[7] += cw[k][7] * bfhi(w.w); }
; #pragma unroll
;             for (int i = 0; i < 8; ++i) *(LAS bf16_t*)(lds + L_XST + (wave * 8 + i) * P64 + lane * 2) = f2bf(siluf_(o[i]));
;         }
;         {
;             const int oc = tid & 15, tk = (tid >> 4) * 2;
;             const float a63s = acv[63]; const float wa = dtv[tk] * __builtin_amdgcn_exp2f(a63s - acv[tk]), wb = dtv[tk + 1] * __builtin_amdgcn_exp2f(a63s - acv[tk + 1]);
;             LAS unsigned char* d = lds + L_BWT + (oc * 8) * P64 + ((((tk >> 3) ^ ((oc >> 1) & 7)) << 4) | ((tk * 2) & 15));
;             *(LAS unsigned*)(d + 0 * P64) = pk2(bflo(bo0.x) * wa, bflo(bo1.x) * wb); *(LAS unsigned*)(d + 1 * P64) = pk2(bfhi(bo0.x) * wa, bfhi(bo1.x) * wb);
;             *(LAS unsigned*)(d + 2 * P64) = pk2(bflo(bo0.y) * wa, bflo(bo1.y) * wb); *(LAS unsigned*)(d + 3 * P64) = pk2(bfhi(bo0.y) * wa, bfhi(bo1.y) * wb);
;             *(LAS unsigned*)(d + 4 * P64) = pk2(bflo(bo0.z) * wa, bflo(bo1.z) * wb); *(LAS unsigned*)(d + 5 * P64) = pk2(bfhi(bo0.z) * wa, bfhi(bo1.z) * wb);
;             *(LAS unsigned*)(d + 6 * P64) = pk2(bflo(bo0.w) * wa, bflo(bo1.w) * wb); *(LAS unsigned*)(d + 7 * P64) = pk2(bfhi(bo0.w) * wa, bfhi(bo1.w) * wb);
;         }
;         {
;             float al[4];
; #pragma unroll
;             for (int j = 0; j < 4; ++j) al[j] = acv[16 * rb + 4 * fq + j];
; #pragma unroll
;             for (int ci = 0; ci < 2; ++ci) { const int cbk = (wave & 1) * 2 + ci; f32x4 acc = (f32x4){0.f, 0.f, 0.f, 0.f};
; #pragma unroll
;                 for (int ks = 0; ks < 4; ++ks) { const bf16x8 av = *(const LAS bf16x8*)(lds + L_CM + (16 * rb + fr) * P128 + (32 * ks + 8 * fq) * 2);
.LBB0_559:
	s_ashr_i32 s22, s15, 7
	s_and_b32 s16, s23, 1
	s_movk_i32 s36, 0x110
	s_lshl_b32 s7, s22, 4
	v_lshl_or_b32 v82, s16, 5, v104
	v_lshrrev_b32_e32 v71, 4, v68
	v_or_b32_e32 v76, s7, v104
	v_mad_u32_u24 v88, v82, s36, v213
	v_mul_lo_u32 v77, v76, s36
	v_lshlrev_b32_e32 v78, 3, v71
	v_readlane_b32 s66, v254, 45
	s_lshl_b32 s15, s23, 4
	v_lshlrev_b32_e32 v105, 2, v71
	s_mul_i32 s65, s23, 0x480
	v_mad_u32_u24 v111, v82, s36, 0
	s_movk_i32 s23, 0xfef2
	v_or_b32_e32 v87, 16, v82
	v_add_u32_e32 v114, 0, v88
	s_lshl_b32 s17, s16, 2
	v_add3_u32 v107, s66, v77, v78
	v_add_u32_e32 v110, 0, v77
	v_or_b32_e32 v77, s7, v105
	v_mad_i32_i24 v112, v82, s23, v111
	v_mad_i32_i24 v115, v87, s23, v114
	s_movk_i32 s23, 0x8e
	v_readlane_b32 s59, v254, 44
	s_or_b32 s56, s17, 1
	v_or_b32_e32 v83, 1, v77
	v_or_b32_e32 v84, 2, v77
	v_or_b32_e32 v85, 3, v77
	v_mad_u32_u24 v90, v82, s23, v112
	v_mov_b32_e32 v91, s66
	v_mad_u32_u24 v93, v87, s23, v115
	s_lshl_b32 s23, s16, 6
	s_lshl_b32 s61, s56, 5
	v_cmp_gt_i32_e64 s[40:41], v82, v77
	v_cmp_gt_i32_e64 s[42:43], v82, v83
	v_cmp_gt_i32_e64 s[44:45], v82, v84
	v_cmp_gt_i32_e64 s[46:47], v82, v85
	v_cmp_gt_i32_e64 s[50:51], v87, v83
	v_mul_u32_u24_e32 v89, 0x90, v82
	v_mad_u32_u24 v91, v82, s36, v91
	v_lshl_add_u32 v92, v82, 1, s59
	v_lshlrev_b32_e32 v102, 3, v83
	v_or_b32_e32 v82, s23, v104
	v_bitop3_b32 v83, s17, v71, 4 bitop3:0x1e
	s_lshl_b32 s56, s56, 4
	v_mad_u32_u24 v138, v82, s74, 0
	v_or_b32_e32 v82, s17, v71
	v_lshlrev_b32_e32 v139, 4, v83
	v_or_b32_e32 v83, s56, v104
	s_or_b32 s57, s17, 2
	v_lshlrev_b32_e32 v137, 4, v82
	v_or_b32_e32 v82, 4, v71
	v_mad_u32_u24 v140, v83, s74, 0
	v_bitop3_b32 v83, s17, v71, 1 bitop3:0x36
	s_lshl_b32 s62, s57, 5
	v_lshlrev_b32_e32 v141, 4, v83
	v_bitop3_b32 v83, s17, v82, 1 bitop3:0x36
	s_lshl_b32 s57, s57, 4
	v_lshlrev_b32_e32 v142, 4, v83
	v_or_b32_e32 v83, s57, v104
	v_or_b32_e32 v74, 1, v66
	v_ashrrev_i32_e32 v80, 6, v94
	v_lshrrev_b32_e32 v81, 1, v94
	s_or_b32 s58, s17, 3
	v_mad_u32_u24 v143, v83, s74, 0
	v_bitop3_b32 v83, s17, v71, 2 bitop3:0x36
	v_mul_lo_u32 v72, v66, s74
	v_mul_lo_u32 v70, v70, s36
	v_mul_lo_u32 v75, v74, s36
	v_bitop3_b32 v80, v81, v80, 7 bitop3:0x6c
	v_lshlrev_b32_e32 v81, 1, v66
	s_lshl_b32 s60, s16, 7
	s_lshl_b32 s63, s58, 5
	v_lshlrev_b32_e32 v144, 4, v83
	v_bitop3_b32 v83, s17, v82, 2 bitop3:0x36
	s_lshl_b32 s58, s58, 4
	v_lshlrev_b32_e32 v66, 2, v66
	s_add_i32 s6, 0, 0x18000
	v_add_u32_e32 v70, 0, v70
	v_add_u32_e32 v75, 0, v75
	v_mul_u32_u24_e32 v79, 0x480, v104
	v_lshlrev_b32_e32 v80, 4, v80
	s_lshl_b32 s21, s22, 6
	v_lshlrev_b32_e32 v76, 7, v76
	s_add_i32 s38, s17, 0
	v_lshlrev_b32_e32 v86, 3, v94
	v_lshlrev_b32_e32 v145, 4, v83
	v_or_b32_e32 v83, s58, v104
	v_bitop3_b32 v71, s17, v71, 3 bitop3:0x36
	v_bitop3_b32 v82, s17, v82, 3 bitop3:0x36
	s_add_i32 s16, s60, 0
	v_and_b32_e32 v66, -8, v66
	v_mov_b32_e32 v99, v1
	v_add_u32_e32 v73, s6, v72
	v_lshlrev_b32_e32 v69, 4, v69
	v_add_u32_e32 v72, s59, v72
	s_add_i32 s20, s6, s15
	v_lshl_add_u32 v78, v68, 1, 0
	v_and_b32_e32 v81, 12, v81
	v_add3_u32 v79, 0, v79, v80
	v_and_b32_e32 v109, 48, v94
	v_and_b32_e32 v148, 15, v94
	v_lshrrev_b32_e32 v150, 2, v148
	v_lshrrev_b32_e32 v151, 3, v148
	v_xor_b32_e32 v150, v150, v151
	v_and_b32_e32 v150, 1, v150
	v_lshlrev_b32_e32 v151, 4, v150
	v_xor_b32_e32 v192, v109, v151
	v_sub_u32_e32 v76, v110, v76
	v_lshl_add_u32 v80, v77, 1, 0
	s_add_i32 s64, s38, 0x1e640
	v_mul_u32_u24_e32 v68, 0x90, v68
	v_mul_lo_u32 v113, v77, s74
	v_cmp_gt_i32_e64 s[48:49], v87, v77
	v_cmp_gt_i32_e64 s[52:53], v87, v84
; __device__ __forceinline__ void ssd_item(const Args& a, LAS unsigned char* lds, int layer, bool is_sample, int b, int h, int seq_row0, int nchunks,
;                                          bf16_t* proj, float* ssq, const int tid) {
;     ...
;             for (int i = 0; i < 8; ++i) *(LAS bf16_t*)(lds + L_XST + (wave * 8 + i) * P64 + lane * 2) = f2bf(siluf_(o[i]));
;         }
;         {
;             const int oc = tid & 15, tk = (tid >> 4) * 2;
;             const float a63s = acv[63]; const float wa = dtv[tk] * __builtin_amdgcn_exp2f(a63s - acv[tk]), wb = dtv[tk + 1] * __builtin_amdgcn_exp2f(a63s - acv[tk + 1]);
;             LAS unsigned char* d = lds + L_BWT + (oc * 8) * P64 + ((((tk >> 3) ^ ((oc >> 1) & 7)) << 4) | ((tk * 2) & 15));
;             *(LAS unsigned*)(d + 0 * P64) = pk2(bflo(bo0.x) * wa, bflo(bo1.x) * wb); *(LAS unsigned*)(d + 1 * P64) = pk2(bfhi(bo0.x) * wa, bfhi(bo1.x) * wb);
;             *(LAS unsigned*)(d + 2 * P64) = pk2(bflo(bo0.y) * wa, bflo(bo1.y) * wb); *(LAS unsigned*)(d + 3 * P64) = pk2(bfhi(bo0.y) * wa, bfhi(bo1.y) * wb);
;             *(LAS unsigned*)(d + 4 * P64) = pk2(bflo(bo0.z) * wa, bflo(bo1.z) * wb); *(LAS unsigned*)(d + 5 * P64) = pk2(bfhi(bo0.z) * wa, bfhi(bo1.z) * wb);
;             *(LAS unsigned*)(d + 6 * P64) = pk2(bflo(bo0.w) * wa, bflo(bo1.w) * wb); *(LAS unsigned*)(d + 7 * P64) = pk2(bfhi(bo0.w) * wa, bfhi(bo1.w) * wb);
;         }
;         {
;             float al[4];
; #pragma unroll
;             for (int j = 0; j < 4; ++j) al[j] = acv[16 * rb + 4 * fq + j];
; #pragma unroll
;             for (int ci = 0; ci < 2; ++ci) { const int cbk = (wave & 1) * 2 + ci; f32x4 acc = (f32x4){0.f, 0.f, 0.f, 0.f};
; #pragma unroll
;                 for (int ks = 0; ks < 4; ++ks) { const bf16x8 av = *(const LAS bf16x8*)(lds + L_CM + (16 * rb + fr) * P128 + (32 * ks + 8 * fq) * 2);
;                     const bf16x8 bv = *(const LAS bf16x8*)(lds + L_BM + (16 * cbk + fr) * P128 + (32 * ks + 8 * fq) * 2); acc = mfma16(av, bv, acc); }
;                 const int s = 16 * cbk + fr; const float as = acv[s], ds = dtv[s];
; #pragma unroll
;                 for (int j = 0; j < 4; ++j) { const int l = 16 * rb + 4 * fq + j;
;                     const float gv = (s <= l) ? acc[j] * __builtin_amdgcn_exp2f(al[j] - as) * ds : 0.f;
;                     *(LAS bf16_t*)(lds + L_G + l * P64 + s * 2) = f2bf(gv); } }
;         }
;         LBAR();
	v_cmp_gt_i32_e64 s[54:55], v87, v85
	v_add_u32_e32 v88, s66, v88
	v_lshl_add_u32 v87, v87, 1, s59
	v_lshlrev_b32_e32 v77, 3, v77
	v_lshlrev_b32_e32 v103, 3, v84
	v_lshlrev_b32_e32 v106, 3, v85
	v_mad_u32_u24 v146, v83, s74, 0
	v_lshlrev_b32_e32 v71, 4, v71
	v_lshlrev_b32_e32 v147, 4, v82
	v_lshlrev_b32_e32 v108, 2, v94
	s_add_i32 s59, 0, 0x1e840
	v_lshl_add_u32 v117, v104, 2, s16
	s_add_i32 s16, s21, 0
	v_add_u32_e32 v120, 0, v66
	v_mov_b32_e32 v66, 0
	v_add_u32_e32 v121, v70, v67
	v_add_u32_e32 v122, v75, v67
	v_add_u32_e32 v67, 0, v86
	v_mov_b32_e32 v97, v1
	v_lshl_add_u64 v[100:101], s[18:19], 0, v[98:99]
	v_cmp_gt_i32_e64 s[4:5], 24, v94
	s_mov_b32 s15, 0
	v_cmp_eq_u32_e64 s[6:7], 0, v104
	v_cmp_gt_i32_e64 s[38:39], 64, v94
	v_add_u32_e32 v116, s59, v108
	v_add_u32_e32 v118, s16, v109
	v_lshl_add_u32 v119, v74, 2, 0
	v_mov_b32_e32 v82, v1
	v_mov_b32_e32 v83, v1
	v_mov_b32_e32 v84, v1
	v_mov_b32_e32 v85, v1
	v_add_u32_e32 v123, s20, v68
	v_add_u32_e32 v124, s65, v78
	v_add_u32_e32 v125, v79, v81
	v_add_u32_e32 v126, v90, v192
	v_add_u32_e32 v127, v91, v192
	v_add_u32_e32 v128, v80, v89
	v_add_u32_e32 v129, v92, v113
	v_add_u32_e32 v130, v93, v192
	v_add_u32_e32 v131, v88, v192
	v_add_u32_e32 v132, v87, v113
	v_add_u32_e32 v133, s64, v77
	v_add_u32_e32 v134, s64, v102
	v_add_u32_e32 v135, s64, v103
	v_add_u32_e32 v136, s64, v106
	v_add_u32_e32 v137, v138, v137
	v_add_u32_e32 v138, v138, v139
	v_add_u32_e32 v139, v140, v141
	v_add_u32_e32 v140, v140, v142
	v_add_u32_e32 v141, v143, v144
	v_add_u32_e32 v142, v143, v145
	v_add_u32_e32 v143, v146, v71
	v_add_u32_e32 v144, v146, v147
	v_add_u32_e32 v145, 0x1e640, v67
	v_add_u32_e32 v146, v73, v69
	v_add_u32_e32 v106, v72, v69
	v_add_u32_e32 v147, v76, v192
	v_bfe_u32 v149, v94, 4, 2
	v_lshrrev_b32_e32 v151, 1, v149
	v_lshlrev_b32_e32 v151, 5, v151
	v_sub_u32_e32 v151, 16, v151
	v_mul_i32_i24_e32 v151, v150, v151
	v_add_u32_e32 v107, v107, v151
	v_add_u32_e32 v128, v128, v151
	v_lshrrev_b32_e32 v151, 1, v149
	v_xor_b32_e32 v151, v151, v149
	v_and_b32_e32 v151, 1, v151
	v_lshrrev_b32_e32 v152, 3, v148
	v_lshlrev_b32_e32 v152, 5, v152
	v_sub_u32_e32 v152, 16, v152
	v_mul_i32_i24_e32 v151, v151, v152
	v_add_u32_e32 v195, v113, v151
	v_bfe_u32 v151, v94, 3, 1
	v_lshlrev_b32_e32 v151, 5, v151
	v_sub_u32_e32 v151, 16, v151
	v_bfe_u32 v152, v94, 6, 1
	v_mul_i32_i24_e32 v153, v152, v151
	v_sub_u32_e32 v152, 1, v152
	v_mul_i32_i24_e32 v152, v152, v151
	v_add_u32_e32 v194, v124, v152
	v_add_u32_e32 v124, v124, v153
	v_and_b32_e32 v151, 1, v94
	v_lshlrev_b32_e32 v151, 5, v151
	v_sub_u32_e32 v151, 16, v151
	v_lshrrev_b32_e32 v152, 4, v94
	v_lshlrev_b32_e32 v152, 1, v152
	v_and_b32_e32 v153, 15, v152
	v_lshrrev_b32_e32 v154, 2, v153
	v_lshrrev_b32_e32 v155, 3, v153
	v_xor_b32_e32 v154, v154, v155
	v_and_b32_e32 v154, 1, v154
	v_mul_i32_i24_e32 v154, v154, v151
	v_add_u32_e32 v121, v121, v154
	v_add_u32_e32 v153, 1, v152
	v_and_b32_e32 v153, 15, v153
	v_lshrrev_b32_e32 v154, 2, v153
	v_lshrrev_b32_e32 v155, 3, v153
	v_xor_b32_e32 v154, v154, v155
	v_and_b32_e32 v154, 1, v154
	v_mul_i32_i24_e32 v154, v154, v151
	v_add_u32_e32 v122, v122, v154
	s_mov_b64 s[16:17], s[26:27]
	s_mov_b32 s64, 0
	v_mov_b32_e32 v67, v66
	v_mov_b32_e32 v68, v66
	v_mov_b32_e32 v69, v66
	v_mov_b32_e32 v78, v66
	v_mov_b32_e32 v79, v66
	v_mov_b32_e32 v80, v66
	v_mov_b32_e32 v81, v66
	v_mov_b32_e32 v70, v66
	v_mov_b32_e32 v71, v66
	v_mov_b32_e32 v72, v66
	v_mov_b32_e32 v73, v66
	v_mov_b32_e32 v74, v66
	v_mov_b32_e32 v75, v66
	v_mov_b32_e32 v76, v66
	v_mov_b32_e32 v77, v66
	s_branch .LBB0_561

; #define LAS __attribute__((address_space(3)))
; __device__ __forceinline__ bf16_t f2bf(float f) { return (bf16_t)(pk2(f, 0.f) & 0xffffu); }
; __device__ __forceinline__ float bflo(unsigned w) { return __uint_as_float(w << 16); }
; __device__ __forceinline__ float bfhi(unsigned w) { return __uint_as_float(w & 0xffff0000u); }
; __device__ __forceinline__ float siluf_(float x) { return x * __builtin_amdgcn_rcpf(1.f + __expf(-x)); }
; __device__ __forceinline__ void ssd_item(const Args& a, LAS unsigned char* lds, int layer, bool is_sample, int b, int h, int seq_row0, int nchunks,
;                                          bf16_t* proj, float* ssq, const int tid) {
;     ...
;         {
;             float o[8];
; #pragma unroll
;             for (int i = 0; i < 8; ++i) o[i] = cb[i];
; #pragma unroll
;             for (int k = 0; k < 4; ++k) { const u32x4 w = *(const LAS u32x4*)(lds + L_XRAW + (lane + k) * P64 + wave * 16);
;                 o[0] += cw[k][0] * bflo(w.x); o[1] += cw[k][1] * bfhi(w.x); o[2] += cw[k][2] * bflo(w.y); o[3] += cw[k][3] * bfhi(w.y);
;                 o[4] += cw[k][4] * bflo(w.z); o[5] += cw[k][5] * bfhi(w.z); o[6] += cw[k][6] * bflo(w.w); o[7] += cw[k][7] * bfhi(w.w); }
; #pragma unroll
;             for (int i = 0; i < 8; ++i) *(LAS bf16_t*)(lds + L_XST + (wave * 8 + i) * P64 + lane * 2) = f2bf(siluf_(o[i]));
;         }
;         {
;             const int oc = tid & 15, tk = (tid >> 4) * 2;
;             const float a63s = acv[63]; const float wa = dtv[tk] * __builtin_amdgcn_exp2f(a63s - acv[tk]), wb = dtv[tk + 1] * __builtin_amdgcn_exp2f(a63s - acv[tk + 1]);
;             LAS unsigned char* d = lds + L_BWT + (oc * 8) * P64 + ((((tk >> 3) ^ ((oc >> 1) & 7)) << 4) | ((tk * 2) & 15));
.LBB0_570:
	ds_read_b128 v[148:151], v123
	ds_read_b128 v[152:155], v123 offset:144
	s_add_i32 s65, s15, 0
	s_add_i32 s65, s65, 0x1c73c
	v_add_u32_e32 v164, v110, v192
	s_waitcnt lgkmcnt(1)
	v_lshlrev_b32_e32 v102, 16, v148
	v_and_b32_e32 v103, 0xffff0000, v148
	v_lshlrev_b32_e32 v148, 16, v149
	v_fma_f32 v156, v8, v148, v40
	v_and_b32_e32 v148, 0xffff0000, v149
	v_fma_f32 v157, v9, v148, v41
	v_lshlrev_b32_e32 v148, 16, v150
	v_fma_f32 v158, v2, v148, v34
	v_and_b32_e32 v148, 0xffff0000, v150
	v_fma_f32 v159, v3, v148, v35
	v_lshlrev_b32_e32 v148, 16, v151
	v_fma_f32 v160, v4, v148, v36
	v_and_b32_e32 v148, 0xffff0000, v151
	v_fma_f32 v102, v6, v102, v38
	v_fma_f32 v161, v5, v148, v37
	s_waitcnt lgkmcnt(0)
	v_lshlrev_b32_e32 v148, 16, v152
	v_fma_f32 v103, v7, v103, v39
	v_fmac_f32_e32 v102, v10, v148
	v_and_b32_e32 v148, 0xffff0000, v152
	v_fmac_f32_e32 v103, v11, v148
	v_lshlrev_b32_e32 v148, 16, v153
	v_fmac_f32_e32 v156, v12, v148
	v_and_b32_e32 v148, 0xffff0000, v153
	v_fmac_f32_e32 v157, v13, v148
	v_lshlrev_b32_e32 v148, 16, v154
	v_fmac_f32_e32 v158, v14, v148
	v_and_b32_e32 v148, 0xffff0000, v154
	v_fmac_f32_e32 v159, v15, v148
	ds_read_b128 v[148:151], v123 offset:288
	v_lshlrev_b32_e32 v152, 16, v155
	v_fmac_f32_e32 v160, v16, v152
	v_and_b32_e32 v152, 0xffff0000, v155
	v_fmac_f32_e32 v161, v17, v152
	ds_read_b128 v[152:155], v123 offset:432
	s_waitcnt lgkmcnt(1)
	v_lshlrev_b32_e32 v162, 16, v148
	v_and_b32_e32 v148, 0xffff0000, v148
	v_fmac_f32_e32 v103, v19, v148
	v_lshlrev_b32_e32 v148, 16, v149
	v_fmac_f32_e32 v156, v20, v148
	v_and_b32_e32 v148, 0xffff0000, v149
	v_fmac_f32_e32 v157, v21, v148
	v_lshlrev_b32_e32 v148, 16, v150
	v_fmac_f32_e32 v158, v22, v148
	v_and_b32_e32 v148, 0xffff0000, v150
	v_fmac_f32_e32 v159, v23, v148
	v_lshlrev_b32_e32 v148, 16, v151
	v_fmac_f32_e32 v160, v24, v148
	v_and_b32_e32 v148, 0xffff0000, v151
	v_fmac_f32_e32 v102, v18, v162
	v_fmac_f32_e32 v161, v25, v148
	s_waitcnt lgkmcnt(0)
	v_lshlrev_b32_e32 v148, 16, v152
	v_fmac_f32_e32 v102, v26, v148
	v_and_b32_e32 v148, 0xffff0000, v152
	v_fmac_f32_e32 v103, v27, v148
	v_lshlrev_b32_e32 v148, 16, v153
	v_fmac_f32_e32 v156, v28, v148
	v_and_b32_e32 v148, 0xffff0000, v153
	v_fmac_f32_e32 v157, v29, v148
	v_lshlrev_b32_e32 v148, 16, v154
	v_fmac_f32_e32 v158, v30, v148
	v_and_b32_e32 v148, 0xffff0000, v154
	v_fmac_f32_e32 v159, v31, v148
	v_mul_f32_e32 v148, 0xbfb8aa3b, v102
	v_exp_f32_e32 v148, v148
	v_mul_f32_e32 v150, 0xbfb8aa3b, v103
	v_exp_f32_e32 v150, v150
	v_lshlrev_b32_e32 v149, 16, v155
	v_add_f32_e32 v148, 1.0, v148
	v_rcp_f32_e32 v148, v148
	v_fmac_f32_e32 v160, v32, v149
	v_and_b32_e32 v149, 0xffff0000, v155
	v_fmac_f32_e32 v161, v33, v149
	v_mul_f32_e32 v102, v102, v148
	v_add_f32_e32 v148, 1.0, v150
	v_mul_f32_e32 v149, 0xbfb8aa3b, v156
	v_rcp_f32_e32 v148, v148
	v_exp_f32_e32 v149, v149
	v_cvt_pk_bf16_f32 v102, v102, v1
	ds_write_b16 v124, v102
	v_mul_f32_e32 v102, v103, v148
	v_add_f32_e32 v103, 1.0, v149
	v_mul_f32_e32 v148, 0xbfb8aa3b, v157
	v_rcp_f32_e32 v103, v103
	v_exp_f32_e32 v148, v148
	v_cvt_pk_bf16_f32 v102, v102, v1
	ds_write_b16 v124, v102 offset:144
	v_mul_f32_e32 v102, v156, v103
	v_add_f32_e32 v103, 1.0, v148
	v_mul_f32_e32 v148, 0xbfb8aa3b, v158
	v_rcp_f32_e32 v103, v103
	v_exp_f32_e32 v148, v148
	v_cvt_pk_bf16_f32 v102, v102, v1
	ds_write_b16 v124, v102 offset:288
	v_mul_f32_e32 v102, v157, v103
	v_add_f32_e32 v103, 1.0, v148
	v_mul_f32_e32 v148, 0xbfb8aa3b, v159
	v_rcp_f32_e32 v103, v103
	v_exp_f32_e32 v148, v148
	v_cvt_pk_bf16_f32 v102, v102, v1
	ds_write_b16 v124, v102 offset:432
	v_mul_f32_e32 v102, v158, v103
	v_add_f32_e32 v103, 1.0, v148
	v_mul_f32_e32 v148, 0xbfb8aa3b, v160
	v_rcp_f32_e32 v103, v103
	v_exp_f32_e32 v148, v148
	v_cvt_pk_bf16_f32 v102, v102, v1
	ds_write_b16 v194, v102 offset:576
	v_mul_f32_e32 v102, v159, v103
	v_add_f32_e32 v103, 1.0, v148
	v_mul_f32_e32 v148, 0xbfb8aa3b, v161
	v_rcp_f32_e32 v103, v103
	v_exp_f32_e32 v148, v148
	v_cvt_pk_bf16_f32 v102, v102, v1
	v_add_u32_e32 v149, s15, v120
	v_add_u32_e32 v151, s15, v119
	ds_write_b16 v194, v102 offset:720
	v_mul_f32_e32 v102, v160, v103
	v_add_f32_e32 v103, 1.0, v148
	v_mov_b32_e32 v148, s65
	v_add_u32_e32 v150, 0x1a640, v149
	v_add_u32_e32 v149, 0x1c640, v149
	v_add_u32_e32 v152, 0x1a640, v151
	v_add_u32_e32 v151, 0x1c640, v151
	ds_read_b32 v148, v148
	ds_read_b32 v150, v150
	ds_read_b32 v149, v149
	ds_read_b32 v152, v152
	ds_read_b32 v151, v151
	v_rcp_f32_e32 v103, v103
	v_cvt_pk_bf16_f32 v102, v102, v1
	ds_write_b16 v194, v102 offset:864
	v_add_u32_e32 v165, s15, v117
	v_mul_f32_e32 v102, v161, v103
	s_waitcnt lgkmcnt(3)
	v_sub_f32_e32 v103, v148, v149
	s_waitcnt lgkmcnt(1)
; #define LAS __attribute__((address_space(3)))
; __device__ __forceinline__ bf16_t f2bf(float f) { return (bf16_t)(pk2(f, 0.f) & 0xffffu); }
; __device__ __forceinline__ void ssd_item(const Args& a, LAS unsigned char* lds, int layer, bool is_sample, int b, int h, int seq_row0, int nchunks,
;                                          bf16_t* proj, float* ssq, const int tid) {
;     ...
;             const int oc = tid & 15, tk = (tid >> 4) * 2;
;             const float a63s = acv[63]; const float wa = dtv[tk] * __builtin_amdgcn_exp2f(a63s - acv[tk]), wb = dtv[tk + 1] * __builtin_amdgcn_exp2f(a63s - acv[tk + 1]);
;             LAS unsigned char* d = lds + L_BWT + (oc * 8) * P64 + ((((tk >> 3) ^ ((oc >> 1) & 7)) << 4) | ((tk * 2) & 15));
;             *(LAS unsigned*)(d + 0 * P64) = pk2(bflo(bo0.x) * wa, bflo(bo1.x) * wb); *(LAS unsigned*)(d + 1 * P64) = pk2(bfhi(bo0.x) * wa, bfhi(bo1.x) * wb);
;             *(LAS unsigned*)(d + 2 * P64) = pk2(bflo(bo0.y) * wa, bflo(bo1.y) * wb); *(LAS unsigned*)(d + 3 * P64) = pk2(bfhi(bo0.y) * wa, bfhi(bo1.y) * wb);
;             *(LAS unsigned*)(d + 4 * P64) = pk2(bflo(bo0.z) * wa, bflo(bo1.z) * wb); *(LAS unsigned*)(d + 5 * P64) = pk2(bfhi(bo0.z) * wa, bfhi(bo1.z) * wb);
;             *(LAS unsigned*)(d + 6 * P64) = pk2(bflo(bo0.w) * wa, bflo(bo1.w) * wb); *(LAS unsigned*)(d + 7 * P64) = pk2(bfhi(bo0.w) * wa, bfhi(bo1.w) * wb);
;         }
;         {
;             float al[4];
; #pragma unroll
;             for (int j = 0; j < 4; ++j) al[j] = acv[16 * rb + 4 * fq + j];
; #pragma unroll
;             for (int ci = 0; ci < 2; ++ci) { const int cbk = (wave & 1) * 2 + ci; f32x4 acc = (f32x4){0.f, 0.f, 0.f, 0.f};
; #pragma unroll
;                 for (int ks = 0; ks < 4; ++ks) { const bf16x8 av = *(const LAS bf16x8*)(lds + L_CM + (16 * rb + fr) * P128 + (32 * ks + 8 * fq) * 2);
;                     const bf16x8 bv = *(const LAS bf16x8*)(lds + L_BM + (16 * cbk + fr) * P128 + (32 * ks + 8 * fq) * 2); acc = mfma16(av, bv, acc); }
;                 const int s = 16 * cbk + fr; const float as = acv[s], ds = dtv[s];
; #pragma unroll
;                 for (int j = 0; j < 4; ++j) { const int l = 16 * rb + 4 * fq + j;
;                     const float gv = (s <= l) ? acc[j] * __builtin_amdgcn_exp2f(al[j] - as) * ds : 0.f;
;                     *(LAS bf16_t*)(lds + L_G + l * P64 + s * 2) = f2bf(gv); } }
;         }
;         LBAR();
	v_sub_f32_e32 v148, v148, v151
	v_exp_f32_e32 v103, v103
	v_exp_f32_e32 v148, v148
	v_cvt_pk_bf16_f32 v102, v102, v1
	ds_write_b16 v194, v102 offset:1008
	v_mul_f32_e32 v102, v150, v103
	v_mul_f32_e32 v103, v152, v148
	v_lshlrev_b32_e32 v148, 16, v58
	v_lshlrev_b32_e32 v149, 16, v62
	v_and_b32_e32 v58, 0xffff0000, v58
	v_and_b32_e32 v62, 0xffff0000, v62
	v_mul_f32_e32 v58, v102, v58
	v_mul_f32_e32 v62, v103, v62
	v_mul_f32_e32 v148, v102, v148
	v_cvt_pk_bf16_f32 v58, v58, v62
	v_add_u32_e32 v62, 0xd000, v125
	v_mul_f32_e32 v149, v103, v149
	v_cvt_pk_bf16_f32 v148, v148, v149
	ds_write2_b32 v62, v148, v58 offset1:36
	v_lshlrev_b32_e32 v58, 16, v59
	v_and_b32_e32 v59, 0xffff0000, v59
	v_mul_f32_e32 v58, v102, v58
	v_lshlrev_b32_e32 v148, 16, v63
	v_mul_f32_e32 v59, v102, v59
	v_and_b32_e32 v63, 0xffff0000, v63
	v_mul_f32_e32 v148, v103, v148
	v_cvt_pk_bf16_f32 v58, v58, v148
	v_mul_f32_e32 v63, v103, v63
	v_cvt_pk_bf16_f32 v59, v59, v63
	ds_write2_b32 v62, v58, v59 offset0:72 offset1:108
	v_lshlrev_b32_e32 v58, 16, v60
	v_lshlrev_b32_e32 v59, 16, v64
	v_mul_f32_e32 v58, v102, v58
	v_mul_f32_e32 v59, v103, v59
	v_cvt_pk_bf16_f32 v58, v58, v59
	v_and_b32_e32 v59, 0xffff0000, v60
	v_mul_f32_e32 v59, v102, v59
	v_and_b32_e32 v60, 0xffff0000, v64
	v_mul_f32_e32 v60, v103, v60
	v_cvt_pk_bf16_f32 v59, v59, v60
	ds_write2_b32 v62, v58, v59 offset0:144 offset1:180
	v_lshlrev_b32_e32 v58, 16, v61
	v_lshlrev_b32_e32 v59, 16, v65
	v_mul_f32_e32 v58, v102, v58
	v_mul_f32_e32 v59, v103, v59
	v_cvt_pk_bf16_f32 v58, v58, v59
	v_and_b32_e32 v59, 0xffff0000, v61
	v_mul_f32_e32 v59, v102, v59
	v_and_b32_e32 v60, 0xffff0000, v65
	v_mul_f32_e32 v60, v103, v60
	v_cvt_pk_bf16_f32 v59, v59, v60
	ds_write2_b32 v62, v58, v59 offset0:216 offset1:252
	ds_read_b128 v[58:61], v164 offset:18432
	v_add_u32_e32 v102, v111, v192
	ds_read_b128 v[62:65], v102 offset:35840
	ds_read_b128 v[148:151], v164 offset:18496
	ds_read_b128 v[152:155], v164 offset:18624
	s_waitcnt lgkmcnt(2)
	v_mfma_f32_16x16x32_bf16 v[58:61], v[58:61], v[62:65], 0
	ds_read_b128 v[62:65], v164 offset:18560
	ds_read_b128 v[156:159], v102 offset:35904
	ds_read_b128 v[160:163], v102 offset:35968
	v_add_u32_e32 v103, s15, v118
	v_add_u32_e32 v103, 0x1c640, v103
	s_waitcnt lgkmcnt(1)
	v_mfma_f32_16x16x32_bf16 v[58:61], v[148:151], v[156:159], v[58:61]
	ds_read_b128 v[148:151], v103
	v_add_u32_e32 v157, 0x1a640, v165
	v_add_u32_e32 v158, 0x1c680, v165
	s_waitcnt lgkmcnt(1)
	v_mfma_f32_16x16x32_bf16 v[58:61], v[62:65], v[160:163], v[58:61]
	v_add_u32_e32 v62, 0x1c640, v165
	ds_read_b32 v156, v62
	ds_read_b128 v[62:65], v102 offset:36032
	ds_read_b32 v102, v157
	ds_read_b32 v169, v158
	s_waitcnt lgkmcnt(2)
	v_mfma_f32_16x16x32_bf16 v[58:61], v[152:155], v[62:65], v[58:61]
	v_sub_f32_e32 v157, v148, v156
	v_exp_f32_e32 v157, v157
	v_sub_f32_e32 v62, v149, v156
	v_exp_f32_e32 v62, v62
	v_add_u32_e32 v63, v112, v195
	s_nop 2
	v_mul_f32_e32 v58, v58, v157
	s_waitcnt lgkmcnt(1)
	v_mul_f32_e32 v58, v102, v58
	v_cndmask_b32_e64 v58, v58, 0, s[40:41]
	v_cvt_pk_bf16_f32 v58, v58, v1
	ds_write_b16 v63, v58 offset:9216
	v_mul_f32_e32 v58, v59, v62
	v_sub_f32_e32 v59, v150, v156
	v_exp_f32_e32 v59, v59
	v_mul_f32_e32 v58, v102, v58
	v_cndmask_b32_e64 v58, v58, 0, s[42:43]
	v_cvt_pk_bf16_f32 v58, v58, v1
	ds_write_b16 v63, v58 offset:9360
	v_mul_f32_e32 v58, v60, v59
	v_sub_f32_e32 v59, v151, v156
	v_exp_f32_e32 v59, v59
	v_mul_f32_e32 v58, v102, v58
	v_cndmask_b32_e64 v58, v58, 0, s[44:45]
	v_cvt_pk_bf16_f32 v58, v58, v1
	ds_write_b16 v63, v58 offset:9504
	v_mul_f32_e32 v58, v61, v59
	v_mul_f32_e32 v58, v102, v58
	v_cndmask_b32_e64 v58, v58, 0, s[46:47]
	v_cvt_pk_bf16_f32 v58, v58, v1
	ds_write_b16 v63, v58 offset:9648
	ds_read_b128 v[58:61], v164 offset:18432
	v_add_u32_e32 v102, v114, v192
	ds_read_b128 v[62:65], v164 offset:18496
	ds_read_b128 v[152:155], v102 offset:35840
	ds_read_b128 v[156:159], v102 offset:35904
	s_waitcnt lgkmcnt(1)
	v_mfma_f32_16x16x32_bf16 v[58:61], v[58:61], v[152:155], 0
	ds_read_b128 v[152:155], v164 offset:18560
	s_waitcnt lgkmcnt(1)
	v_mfma_f32_16x16x32_bf16 v[58:61], v[62:65], v[156:159], v[58:61]
	ds_read_b128 v[62:65], v102 offset:35968
	ds_read_b128 v[156:159], v164 offset:18624
	ds_read_b128 v[160:163], v102 offset:36032
	s_waitcnt lgkmcnt(2)
	v_mfma_f32_16x16x32_bf16 v[58:61], v[152:155], v[62:65], v[58:61]
	v_sub_f32_e32 v63, v148, v169
	v_add_u32_e32 v62, 0x1a680, v165
	v_exp_f32_e32 v63, v63
	s_waitcnt lgkmcnt(0)
	v_mfma_f32_16x16x32_bf16 v[58:61], v[156:159], v[160:163], v[58:61]
	ds_read_b32 v62, v62
	v_add_u32_e32 v64, v115, v195
	s_nop 5
	v_mul_f32_e32 v58, v58, v63
	v_sub_f32_e32 v63, v149, v169
	v_exp_f32_e32 v63, v63
	s_waitcnt lgkmcnt(0)
	v_mul_f32_e32 v58, v62, v58
	v_cndmask_b32_e64 v58, v58, 0, s[48:49]
	v_cvt_pk_bf16_f32 v58, v58, v1
	ds_write_b16 v64, v58 offset:9216
	v_mul_f32_e32 v58, v59, v63
	v_sub_f32_e32 v59, v150, v169
	v_exp_f32_e32 v59, v59
	v_mul_f32_e32 v58, v62, v58
	v_cndmask_b32_e64 v58, v58, 0, s[50:51]
	v_cvt_pk_bf16_f32 v58, v58, v1
	ds_write_b16 v64, v58 offset:9360
	v_mul_f32_e32 v58, v60, v59
	v_sub_f32_e32 v59, v151, v169
	v_exp_f32_e32 v59, v59
	v_mul_f32_e32 v58, v62, v58
	v_cndmask_b32_e64 v58, v58, 0, s[52:53]
	v_cvt_pk_bf16_f32 v58, v58, v1
	ds_write_b16 v64, v58 offset:9504
	v_mul_f32_e32 v58, v61, v59
	v_mul_f32_e32 v58, v62, v58
	v_cndmask_b32_e64 v58, v58, 0, s[54:55]
	v_cvt_pk_bf16_f32 v58, v58, v1
	ds_write_b16 v64, v58 offset:9648
	s_waitcnt lgkmcnt(0)
	s_barrier
; __device__ __forceinline__ void ssd_item(const Args& a, LAS unsigned char* lds, int layer, bool is_sample, int b, int h, int seq_row0, int nchunks,
;                                          bf16_t* proj, float* ssq, const int tid) {
;     ...
;         {
;             float sq[4] = {0.f, 0.f, 0.f, 0.f}, el[4];
; #pragma unroll
;             for (int j = 0; j < 4; ++j) el[j] = __builtin_amdgcn_exp2f(acv[16 * rb + 4 * fq + j]);
; #pragma unroll
;             for (int ci = 0; ci < 2; ++ci) { const int cbk = (wave & 1) * 2 + ci; f32x4 acc = (f32x4){0.f, 0.f, 0.f, 0.f}, acp = (f32x4){0.f, 0.f, 0.f, 0.f};
; #pragma unroll
;                 for (int ks = 0; ks < 2; ++ks) { const bf16x8 av = *(const LAS bf16x8*)(lds + L_G + (16 * rb + fr) * P64 + (32 * ks + 8 * fq) * 2);
;                     const bf16x8 bv = *(const LAS bf16x8*)(lds + L_XST + (16 * cbk + fr) * P64 + (32 * ks + 8 * fq) * 2); acc = mfma16(av, bv, acc); }
; #pragma unroll
;                 for (int ks = 0; ks < 4; ++ks) { const bf16x8 av = *(const LAS bf16x8*)(lds + L_CM + (16 * rb + fr) * P128 + (32 * ks + 8 * fq) * 2);
;                     const bf16x8 bv = *(const LAS bf16x8*)(lds + L_ST + (16 * cbk + fr) * P128 + (32 * ks + 8 * fq) * 2); acp = mfma16(av, bv, acp); }
;                 const int p = 16 * cbk + fr;
;                 const u32x2 xs4 = *(const LAS u32x2*)(lds + L_XST + p * P64 + (16 * rb + 4 * fq) * 2);
;                 const float xsv[4] = {bflo(xs4.x), bfhi(xs4.x), bflo(xs4.y), bfhi(xs4.y)};
; #pragma unroll
;                 for (int j = 0; j < 4; ++j) { const int l = 16 * rb + 4 * fq + j;
;                     LAS bf16_t* zp = (LAS bf16_t*)(lds + L_ZT + l * P64 + p * 2);
;                     const float z = bf2f(*zp);
;                     const float yg = (acc[j] + el[j] * acp[j] + xsv[j] * dsk) * siluf_(z);
;                     *zp = f2bf(yg); sq[j] += yg * yg; } }
; #pragma unroll
;             for (int j = 0; j < 4; ++j) { const float v = row16_sum(sq[j]);
;                 if (fr == 0) ssqp[(16 * rb + 4 * fq + j) * 2 + (wave & 1)] = v; }
;             const float dec = __builtin_amdgcn_exp2f(acv[63]);
; #pragma unroll
;             for (int i = 0; i < 4; ++i) { st[i] = st[i] * dec;
; #pragma unroll
;                 for (int ks = 0; ks < 2; ++ks) { const bf16x8 av = *(const LAS bf16x8*)(lds + L_XST + (16 * pb + fr) * P64 + (32 * ks + 8 * fq) * 2);
	v_mov_b32_e32 v58, s65
	ds_read_b32 v102, v58
	ds_read_b128 v[148:151], v147
	ds_read_b128 v[176:179], v137 offset:53248
	ds_read_b128 v[180:183], v139 offset:53248
	ds_read_b128 v[184:187], v141 offset:53248
	ds_read_b128 v[188:191], v143 offset:53248
	ds_read_b128 v[152:155], v147 offset:64
	ds_read_b128 v[216:219], v138 offset:53248
	ds_read_b128 v[220:223], v140 offset:53248
	ds_read_b128 v[224:227], v142 offset:53248
	ds_read_b128 v[228:231], v144 offset:53248
	ds_read_b128 v[156:159], v147 offset:9216
	ds_read_b128 v[160:163], v147 offset:9280
	s_waitcnt lgkmcnt(12)
	v_exp_f32_e32 v102, v102
	s_nop 0
	v_pk_mul_f32 v[66:67], v[66:67], v[102:103] op_sel_hi:[1,0]
	v_pk_mul_f32 v[68:69], v[68:69], v[102:103] op_sel_hi:[1,0]
	v_pk_mul_f32 v[78:79], v[78:79], v[102:103] op_sel_hi:[1,0]
	v_pk_mul_f32 v[80:81], v[80:81], v[102:103] op_sel_hi:[1,0]
	v_pk_mul_f32 v[70:71], v[70:71], v[102:103] op_sel_hi:[1,0]
	v_pk_mul_f32 v[72:73], v[72:73], v[102:103] op_sel_hi:[1,0]
	v_pk_mul_f32 v[74:75], v[74:75], v[102:103] op_sel_hi:[1,0]
	v_pk_mul_f32 v[76:77], v[76:77], v[102:103] op_sel_hi:[1,0]
	s_waitcnt lgkmcnt(11)
	s_waitcnt lgkmcnt(10)
	v_mfma_f32_16x16x32_bf16 v[66:69], v[176:179], v[148:151], v[66:69]
	s_waitcnt lgkmcnt(9)
	v_mfma_f32_16x16x32_bf16 v[78:81], v[180:183], v[148:151], v[78:81]
	s_waitcnt lgkmcnt(8)
	v_mfma_f32_16x16x32_bf16 v[70:73], v[184:187], v[148:151], v[70:73]
	s_waitcnt lgkmcnt(7)
	v_mfma_f32_16x16x32_bf16 v[74:77], v[188:191], v[148:151], v[74:77]
	ds_read_b128 v[232:235], v164 offset:18432
	ds_read_b128 v[236:239], v164 offset:18496
	ds_read_b128 v[240:243], v164 offset:18560
	ds_read_b128 v[244:247], v164 offset:18624
	ds_read_b128 v[176:179], v127
	ds_read_b128 v[180:183], v127 offset:64
	ds_read_b128 v[184:187], v127 offset:128
	ds_read_b128 v[188:191], v127 offset:192
	s_waitcnt lgkmcnt(14)
	s_waitcnt lgkmcnt(13)
	v_mfma_f32_16x16x32_bf16 v[66:69], v[216:219], v[152:155], v[66:69]
	s_waitcnt lgkmcnt(12)
	v_mfma_f32_16x16x32_bf16 v[78:81], v[220:223], v[152:155], v[78:81]
	s_waitcnt lgkmcnt(11)
	v_mfma_f32_16x16x32_bf16 v[70:73], v[224:227], v[152:155], v[70:73]
	s_waitcnt lgkmcnt(10)
	v_mfma_f32_16x16x32_bf16 v[74:77], v[228:231], v[152:155], v[74:77]
	ds_read_b128 v[148:151], v126
	ds_read_b128 v[152:155], v126 offset:64
	ds_read_b64 v[248:249], v128
	ds_read_b64 v[250:251], v128 offset:2304
	s_waitcnt lgkmcnt(7)
	v_mfma_f32_16x16x32_bf16 v[176:179], v[232:235], v[176:179], 0
	ds_read_b128 v[216:219], v131
	ds_read_b128 v[220:223], v131 offset:64
	ds_read_b128 v[224:227], v131 offset:128
	ds_read_b128 v[228:231], v131 offset:192
	ds_read_b128 v[58:61], v130
	ds_read_b128 v[62:65], v130 offset:64
	s_waitcnt lgkmcnt(12)
	v_mfma_f32_16x16x32_bf16 v[176:179], v[236:239], v[180:183], v[176:179]
	s_waitcnt lgkmcnt(11)
	v_mfma_f32_16x16x32_bf16 v[176:179], v[240:243], v[184:187], v[176:179]
	s_waitcnt lgkmcnt(10)
	v_mfma_f32_16x16x32_bf16 v[176:179], v[244:247], v[188:191], v[176:179]
	s_waitcnt lgkmcnt(9)
	v_mfma_f32_16x16x32_bf16 v[148:151], v[156:159], v[148:151], 0
	ds_read_u16 v165, v129
	ds_read_u16 v169, v129 offset:144
	ds_read_u16 v170, v129 offset:288
	ds_read_u16 v171, v129 offset:432
	s_waitcnt lgkmcnt(12)
	v_mfma_f32_16x16x32_bf16 v[148:151], v[160:163], v[152:155], v[148:151]
	s_waitcnt lgkmcnt(9)
	v_mfma_f32_16x16x32_bf16 v[216:219], v[232:235], v[216:219], 0
	ds_read_b128 v[232:235], v103
	ds_read_u16 v172, v132
	ds_read_u16 v173, v132 offset:144
	ds_read_u16 v215, v132 offset:288
	ds_read_u16 v102, v132 offset:432
	s_waitcnt lgkmcnt(13)
	v_mfma_f32_16x16x32_bf16 v[216:219], v[236:239], v[220:223], v[216:219]
	s_waitcnt lgkmcnt(10)
	v_mfma_f32_16x16x32_bf16 v[58:61], v[156:159], v[58:61], 0
	s_waitcnt lgkmcnt(9)
	v_mfma_f32_16x16x32_bf16 v[58:61], v[160:163], v[62:65], v[58:61]
	s_waitcnt lgkmcnt(4)
; #define LAS __attribute__((address_space(3)))
; __device__ __forceinline__ bf16_t f2bf(float f) { return (bf16_t)(pk2(f, 0.f) & 0xffffu); }
; __device__ __forceinline__ float bflo(unsigned w) { return __uint_as_float(w << 16); }
; __device__ __forceinline__ float bfhi(unsigned w) { return __uint_as_float(w & 0xffff0000u); }
; __device__ __forceinline__ float bf2f(bf16_t h) { return __uint_as_float(((unsigned)h) << 16); }
; __device__ __forceinline__ float siluf_(float x) { return x * __builtin_amdgcn_rcpf(1.f + __expf(-x)); }
; __device__ __forceinline__ f32x4 mfma16(bf16x8 a, bf16x8 b, f32x4 c) { return __builtin_amdgcn_mfma_f32_16x16x32_bf16(a, b, c, 0, 0, 0); }
; __device__ __forceinline__ void ssd_item(const Args& a, LAS unsigned char* lds, int layer, bool is_sample, int b, int h, int seq_row0, int nchunks,
;                                          bf16_t* proj, float* ssq, const int tid) {
;     ...
;                 const u32x2 xs4 = *(const LAS u32x2*)(lds + L_XST + p * P64 + (16 * rb + 4 * fq) * 2);
;                 const float xsv[4] = {bflo(xs4.x), bfhi(xs4.x), bflo(xs4.y), bfhi(xs4.y)};
; #pragma unroll
;                 for (int j = 0; j < 4; ++j) { const int l = 16 * rb + 4 * fq + j;
;                     LAS bf16_t* zp = (LAS bf16_t*)(lds + L_ZT + l * P64 + p * 2);
;                     const float z = bf2f(*zp);
;                     const float yg = (acc[j] + el[j] * acp[j] + xsv[j] * dsk) * siluf_(z);
;                     *zp = f2bf(yg); sq[j] += yg * yg; } }
; #pragma unroll
;             for (int j = 0; j < 4; ++j) { const float v = row16_sum(sq[j]);
;                 if (fr == 0) ssqp[(16 * rb + 4 * fq + j) * 2 + (wave & 1)] = v; }
;             const float dec = __builtin_amdgcn_exp2f(acv[63]);
; #pragma unroll
;             for (int i = 0; i < 4; ++i) { st[i] = st[i] * dec;
; #pragma unroll
;                 for (int ks = 0; ks < 2; ++ks) { const bf16x8 av = *(const LAS bf16x8*)(lds + L_XST + (16 * pb + fr) * P64 + (32 * ks + 8 * fq) * 2);
;                     const bf16x8 bv = *(const LAS bf16x8*)(lds + L_BWT + (16 * (nb0 + i) + fr) * P64 + (((4 * ks + fq) ^ ((nb0 + i) & 7)) << 4)); st[i] = mfma16(bv, av, st[i]); } }
;         }
;         LBAR();
;         if (tid < 64) ((LAS float*)(lds + L_SSQA))[c * 64 + tid] = ssqp[tid * 2] + ssqp[tid * 2 + 1];
	v_exp_f32_e32 v232, v232
	v_exp_f32_e32 v233, v233
	v_exp_f32_e32 v234, v234
	v_exp_f32_e32 v235, v235
	v_mfma_f32_16x16x32_bf16 v[216:219], v[240:243], v[224:227], v[216:219]
	v_lshlrev_b32_e32 v180, 16, v248
	v_and_b32_e32 v181, 0xffff0000, v248
	v_lshlrev_b32_e32 v182, 16, v249
	v_and_b32_e32 v183, 0xffff0000, v249
	v_mfma_f32_16x16x32_bf16 v[216:219], v[244:247], v[228:231], v[216:219]
	v_lshlrev_b32_e32 v165, 16, v165
	v_mul_f32_e32 v188, 0xbfb8aa3b, v165
	v_exp_f32_e32 v188, v188
	v_lshlrev_b32_e32 v169, 16, v169
	v_mul_f32_e32 v189, 0xbfb8aa3b, v169
	v_exp_f32_e32 v189, v189
	v_lshlrev_b32_e32 v170, 16, v170
	v_mul_f32_e32 v190, 0xbfb8aa3b, v170
	v_exp_f32_e32 v190, v190
	v_lshlrev_b32_e32 v171, 16, v171
	v_mul_f32_e32 v191, 0xbfb8aa3b, v171
	v_exp_f32_e32 v191, v191
	v_fma_f32 v148, v232, v176, v148
	v_fmac_f32_e32 v148, v95, v180
	v_fma_f32 v149, v233, v177, v149
	v_fmac_f32_e32 v149, v95, v181
	v_fma_f32 v150, v234, v178, v150
	v_fmac_f32_e32 v150, v95, v182
	v_fma_f32 v151, v235, v179, v151
	v_fmac_f32_e32 v151, v95, v183
	v_add_f32_e32 v188, 1.0, v188
	v_rcp_f32_e32 v188, v188
	v_add_f32_e32 v189, 1.0, v189
	v_rcp_f32_e32 v189, v189
	v_add_f32_e32 v190, 1.0, v190
	v_rcp_f32_e32 v190, v190
	v_add_f32_e32 v191, 1.0, v191
	v_rcp_f32_e32 v191, v191
	v_mul_f32_e32 v188, v188, v165
	v_mul_f32_e32 v152, v148, v188
	v_mul_f32_e32 v189, v189, v169
	v_mul_f32_e32 v153, v149, v189
	v_mul_f32_e32 v190, v190, v170
	v_mul_f32_e32 v154, v150, v190
	v_mul_f32_e32 v191, v191, v171
	v_mul_f32_e32 v155, v151, v191
	v_cvt_pk_bf16_f32 v176, v152, v1
	ds_write_b16 v129, v176
	v_cvt_pk_bf16_f32 v177, v153, v1
	ds_write_b16 v129, v177 offset:144
	v_cvt_pk_bf16_f32 v178, v154, v1
	ds_write_b16 v129, v178 offset:288
	v_cvt_pk_bf16_f32 v179, v155, v1
	ds_write_b16 v129, v179 offset:432
	v_lshlrev_b32_e32 v184, 16, v250
	v_and_b32_e32 v185, 0xffff0000, v250
	v_lshlrev_b32_e32 v186, 16, v251
	v_and_b32_e32 v187, 0xffff0000, v251
	s_waitcnt lgkmcnt(7)
	v_lshlrev_b32_e32 v172, 16, v172
	v_mul_f32_e32 v188, 0xbfb8aa3b, v172
	v_exp_f32_e32 v188, v188
	s_waitcnt lgkmcnt(6)
	v_lshlrev_b32_e32 v173, 16, v173
	v_mul_f32_e32 v189, 0xbfb8aa3b, v173
	v_exp_f32_e32 v189, v189
	s_waitcnt lgkmcnt(5)
	v_lshlrev_b32_e32 v215, 16, v215
	v_mul_f32_e32 v190, 0xbfb8aa3b, v215
	v_exp_f32_e32 v190, v190
	s_waitcnt lgkmcnt(4)
	v_lshlrev_b32_e32 v102, 16, v102
	v_mul_f32_e32 v191, 0xbfb8aa3b, v102
	v_exp_f32_e32 v191, v191
	v_fma_f32 v58, v232, v216, v58
	v_fmac_f32_e32 v58, v95, v184
	v_fma_f32 v59, v233, v217, v59
	v_fmac_f32_e32 v59, v95, v185
	v_fma_f32 v60, v234, v218, v60
	v_fmac_f32_e32 v60, v95, v186
	v_fma_f32 v61, v235, v219, v61
	v_fmac_f32_e32 v61, v95, v187
	v_add_f32_e32 v188, 1.0, v188
	v_rcp_f32_e32 v188, v188
	v_add_f32_e32 v189, 1.0, v189
	v_rcp_f32_e32 v189, v189
	v_add_f32_e32 v190, 1.0, v190
	v_rcp_f32_e32 v190, v190
	v_add_f32_e32 v191, 1.0, v191
	v_rcp_f32_e32 v191, v191
	v_mul_f32_e32 v188, v188, v172
	v_mul_f32_e32 v62, v58, v188
	v_mul_f32_e32 v189, v189, v173
	v_mul_f32_e32 v63, v59, v189
	v_mul_f32_e32 v190, v190, v215
	v_mul_f32_e32 v64, v60, v190
	v_mul_f32_e32 v191, v191, v102
	v_mul_f32_e32 v65, v61, v191
	v_cvt_pk_bf16_f32 v220, v62, v1
	ds_write_b16 v132, v220
	v_cvt_pk_bf16_f32 v221, v63, v1
	ds_write_b16 v132, v221 offset:144
	v_cvt_pk_bf16_f32 v222, v64, v1
	ds_write_b16 v132, v222 offset:288
	v_cvt_pk_bf16_f32 v223, v65, v1
	ds_write_b16 v132, v223 offset:432
	v_mul_f32_e32 v156, v62, v62
	v_fmac_f32_e32 v156, v152, v152
	v_mul_f32_e32 v157, v63, v63
	v_fmac_f32_e32 v157, v153, v153
	v_mul_f32_e32 v158, v64, v64
	v_fmac_f32_e32 v158, v154, v154
	v_mul_f32_e32 v159, v65, v65
	v_fmac_f32_e32 v159, v155, v155
	v_add_f32_dpp v156, v156, v156 quad_perm:[1,0,3,2] row_mask:0xf bank_mask:0xf bound_ctrl:1
	v_add_f32_dpp v157, v157, v157 quad_perm:[1,0,3,2] row_mask:0xf bank_mask:0xf bound_ctrl:1
	v_add_f32_dpp v158, v158, v158 quad_perm:[1,0,3,2] row_mask:0xf bank_mask:0xf bound_ctrl:1
	v_add_f32_dpp v159, v159, v159 quad_perm:[1,0,3,2] row_mask:0xf bank_mask:0xf bound_ctrl:1
	v_add_f32_dpp v156, v156, v156 quad_perm:[2,3,0,1] row_mask:0xf bank_mask:0xf bound_ctrl:1
	v_add_f32_dpp v157, v157, v157 quad_perm:[2,3,0,1] row_mask:0xf bank_mask:0xf bound_ctrl:1
	v_add_f32_dpp v158, v158, v158 quad_perm:[2,3,0,1] row_mask:0xf bank_mask:0xf bound_ctrl:1
	v_add_f32_dpp v159, v159, v159 quad_perm:[2,3,0,1] row_mask:0xf bank_mask:0xf bound_ctrl:1
	v_add_f32_dpp v156, v156, v156 row_half_mirror row_mask:0xf bank_mask:0xf bound_ctrl:1
	v_add_f32_dpp v157, v157, v157 row_half_mirror row_mask:0xf bank_mask:0xf bound_ctrl:1
	v_add_f32_dpp v158, v158, v158 row_half_mirror row_mask:0xf bank_mask:0xf bound_ctrl:1
	v_add_f32_dpp v159, v159, v159 row_half_mirror row_mask:0xf bank_mask:0xf bound_ctrl:1
	v_mov_b32_dpp v160, v156 row_mirror row_mask:0xf bank_mask:0xf bound_ctrl:1
	v_mov_b32_dpp v161, v157 row_mirror row_mask:0xf bank_mask:0xf bound_ctrl:1
	v_mov_b32_dpp v162, v158 row_mirror row_mask:0xf bank_mask:0xf bound_ctrl:1
	v_mov_b32_dpp v163, v159 row_mirror row_mask:0xf bank_mask:0xf bound_ctrl:1
	s_and_saveexec_b64 s[20:21], s[6:7]
	v_add_f32_e32 v156, v156, v160
	v_add_f32_e32 v157, v157, v161
	v_add_f32_e32 v158, v158, v162
	v_add_f32_e32 v159, v159, v163
	ds_write_b32 v133, v156
	ds_write_b32 v134, v157
	ds_write_b32 v135, v158
	ds_write_b32 v136, v159
	s_or_b64 exec, exec, s[20:21]
	s_waitcnt lgkmcnt(0)
	s_barrier
	s_and_saveexec_b64 s[20:21], s[38:39]
	s_cbranch_execz .LBB0_560
	s_nop 1
	ds_read_b64 v[58:59], v145
	v_add_u32_e32 v60, s15, v116
	s_waitcnt lgkmcnt(0)
	v_add_f32_e32 v58, v58, v59
	ds_write_b32 v60, v58
	s_branch .LBB0_560
